# rmsnorm/out-proj overlap: workgroups with a third GEMM tile skip the rmsnorm phase; their rows are redistributed as one extra iteration on 72 other workgroups
# speedup vs baseline: 1.0197x; 1.0142x over previous
.LBB0_983:
	ds_read_b128 v[148:151], v143
	ds_read_b128 v[152:155], v143 offset:1024
	ds_read_b128 v[156:159], v143 offset:2048
	ds_read_b128 v[160:163], v143 offset:3072
	s_add_u32 s22, s20, 0xfffc0080
	s_addc_u32 s23, s21, -1
	s_cmp_eq_u32 s50, 12
	s_cselect_b32 s25, s9, s23
	s_cselect_b32 s24, s46, s22
	s_cselect_b32 s23, s15, s49
	s_cselect_b32 s22, s47, s48
	s_mov_b32 m0, s42
	v_lshl_add_u64 v[196:197], s[20:21], 0, v[134:135]
	ds_read_b128 v[164:167], v142
	ds_read_b128 v[168:171], v142 offset:1024
	ds_read_b128 v[172:175], v142 offset:2048
	ds_read_b128 v[176:179], v142 offset:3072
	ds_read_b128 v[180:183], v142 offset:4096
	ds_read_b128 v[184:187], v142 offset:5120
	ds_read_b128 v[188:191], v142 offset:6144
	ds_read_b128 v[192:195], v142 offset:7168
	global_load_lds_dwordx4 v[196:197], off
	v_lshl_add_u64 v[196:197], s[20:21], 0, v[136:137]
	s_mov_b32 m0, s43
	s_nop 0
	global_load_lds_dwordx4 v[196:197], off
	s_waitcnt lgkmcnt(8)
	s_barrier
	s_waitcnt lgkmcnt(0)
	s_setprio 1
	s_waitcnt lgkmcnt(0)
	v_mfma_f32_16x16x32_bf16 v[124:127], v[148:151], v[164:167], v[124:127]
	v_mfma_f32_16x16x32_bf16 v[120:123], v[156:159], v[164:167], v[120:123]
	v_mfma_f32_16x16x32_bf16 v[116:119], v[148:151], v[172:175], v[116:119]
	v_mfma_f32_16x16x32_bf16 v[112:115], v[156:159], v[172:175], v[112:115]
	v_mfma_f32_16x16x32_bf16 v[108:111], v[148:151], v[180:183], v[108:111]
	v_mfma_f32_16x16x32_bf16 v[104:107], v[156:159], v[180:183], v[104:107]
	v_mfma_f32_16x16x32_bf16 v[100:103], v[148:151], v[188:191], v[100:103]
	v_mfma_f32_16x16x32_bf16 v[96:99], v[156:159], v[188:191], v[96:99]
	v_mfma_f32_16x16x32_bf16 v[124:127], v[152:155], v[168:171], v[124:127]
	v_mfma_f32_16x16x32_bf16 v[120:123], v[160:163], v[168:171], v[120:123]
	v_mfma_f32_16x16x32_bf16 v[116:119], v[152:155], v[176:179], v[116:119]
	v_mfma_f32_16x16x32_bf16 v[112:115], v[160:163], v[176:179], v[112:115]
	v_mfma_f32_16x16x32_bf16 v[108:111], v[152:155], v[184:187], v[108:111]
	v_mfma_f32_16x16x32_bf16 v[104:107], v[160:163], v[184:187], v[104:107]
	v_mfma_f32_16x16x32_bf16 v[100:103], v[152:155], v[192:195], v[100:103]
	v_mfma_f32_16x16x32_bf16 v[96:99], v[160:163], v[192:195], v[96:99]
	s_setprio 0
	s_barrier
	s_mov_b32 m0, s27
	v_lshl_add_u64 v[196:197], s[22:23], 0, v[130:131]
	ds_read_b128 v[200:203], v144
	ds_read_b128 v[204:207], v144 offset:1024
	ds_read_b128 v[208:211], v144 offset:2048
	ds_read_b128 v[212:215], v144 offset:3072
	global_load_lds_dwordx4 v[196:197], off
	v_lshl_add_u64 v[216:217], s[22:23], 0, v[128:129]
	s_mov_b32 m0, s28
	s_nop 0
	global_load_lds_dwordx4 v[216:217], off
	s_barrier
	s_waitcnt lgkmcnt(0)
	s_setprio 1
	s_waitcnt lgkmcnt(0)
	v_mfma_f32_16x16x32_bf16 v[92:95], v[200:203], v[164:167], v[92:95]
	v_mfma_f32_16x16x32_bf16 v[88:91], v[208:211], v[164:167], v[88:91]
	v_mfma_f32_16x16x32_bf16 v[84:87], v[200:203], v[172:175], v[84:87]
	v_mfma_f32_16x16x32_bf16 v[80:83], v[208:211], v[172:175], v[80:83]
	v_mfma_f32_16x16x32_bf16 v[76:79], v[200:203], v[180:183], v[76:79]
	v_mfma_f32_16x16x32_bf16 v[72:75], v[208:211], v[180:183], v[72:75]
	v_mfma_f32_16x16x32_bf16 v[68:71], v[200:203], v[188:191], v[68:71]
	v_mfma_f32_16x16x32_bf16 v[64:67], v[208:211], v[188:191], v[64:67]
	v_mfma_f32_16x16x32_bf16 v[92:95], v[204:207], v[168:171], v[92:95]
	v_mfma_f32_16x16x32_bf16 v[88:91], v[212:215], v[168:171], v[88:91]
	v_mfma_f32_16x16x32_bf16 v[84:87], v[204:207], v[176:179], v[84:87]
	v_mfma_f32_16x16x32_bf16 v[80:83], v[212:215], v[176:179], v[80:83]
	v_mfma_f32_16x16x32_bf16 v[76:79], v[204:207], v[184:187], v[76:79]
	v_mfma_f32_16x16x32_bf16 v[72:75], v[212:215], v[184:187], v[72:75]
	v_mfma_f32_16x16x32_bf16 v[68:71], v[204:207], v[192:195], v[68:71]
	v_mfma_f32_16x16x32_bf16 v[64:67], v[212:215], v[192:195], v[64:67]
	s_setprio 0
	s_mov_b32 m0, s86
	v_lshl_add_u64 v[218:219], s[24:25], 0, v[130:131]
	s_barrier
	ds_read_b128 v[164:167], v142 offset:16384
	ds_read_b128 v[168:171], v142 offset:17408
	ds_read_b128 v[172:175], v142 offset:18432
	ds_read_b128 v[176:179], v142 offset:19456
	ds_read_b128 v[180:183], v142 offset:20480
	ds_read_b128 v[184:187], v142 offset:21504
	ds_read_b128 v[188:191], v142 offset:22528
	ds_read_b128 v[192:195], v142 offset:23552
	global_load_lds_dwordx4 v[218:219], off
	v_lshl_add_u64 v[220:221], s[24:25], 0, v[128:129]
	s_mov_b32 m0, s29
	s_nop 0
	global_load_lds_dwordx4 v[220:221], off
	s_barrier
	s_waitcnt lgkmcnt(0)
	s_setprio 1
	s_waitcnt lgkmcnt(0)
	v_mfma_f32_16x16x32_bf16 v[60:63], v[148:151], v[164:167], v[60:63]
	v_mfma_f32_16x16x32_bf16 v[56:59], v[156:159], v[164:167], v[56:59]
	v_mfma_f32_16x16x32_bf16 v[52:55], v[148:151], v[172:175], v[52:55]
	v_mfma_f32_16x16x32_bf16 v[48:51], v[156:159], v[172:175], v[48:51]
	v_mfma_f32_16x16x32_bf16 v[44:47], v[148:151], v[180:183], v[44:47]
	v_mfma_f32_16x16x32_bf16 v[40:43], v[156:159], v[180:183], v[40:43]
	v_mfma_f32_16x16x32_bf16 v[36:39], v[148:151], v[188:191], v[36:39]
	v_mfma_f32_16x16x32_bf16 v[32:35], v[156:159], v[188:191], v[32:35]
	v_mfma_f32_16x16x32_bf16 v[60:63], v[152:155], v[168:171], v[60:63]
	v_mfma_f32_16x16x32_bf16 v[56:59], v[160:163], v[168:171], v[56:59]
	v_mfma_f32_16x16x32_bf16 v[52:55], v[152:155], v[176:179], v[52:55]
	v_mfma_f32_16x16x32_bf16 v[48:51], v[160:163], v[176:179], v[48:51]
	v_mfma_f32_16x16x32_bf16 v[44:47], v[152:155], v[184:187], v[44:47]
	v_mfma_f32_16x16x32_bf16 v[40:43], v[160:163], v[184:187], v[40:43]
	v_mfma_f32_16x16x32_bf16 v[36:39], v[152:155], v[192:195], v[36:39]
	v_mfma_f32_16x16x32_bf16 v[32:35], v[160:163], v[192:195], v[32:35]
	s_setprio 0
	s_barrier
	s_add_u32 s52, s22, 0x40000
	s_addc_u32 s53, s23, 0
	s_mov_b32 m0, s30
	v_lshl_add_u64 v[148:149], s[52:53], 0, v[130:131]
	global_load_lds_dwordx4 v[148:149], off
	v_lshl_add_u64 v[148:149], s[52:53], 0, v[128:129]
	s_mov_b32 m0, s31
	s_nop 0
	global_load_lds_dwordx4 v[148:149], off
	s_waitcnt vmcnt(6)
	s_barrier
	s_setprio 1
	v_mfma_f32_16x16x32_bf16 v[28:31], v[200:203], v[164:167], v[28:31]
	v_mfma_f32_16x16x32_bf16 v[24:27], v[208:211], v[164:167], v[24:27]
	v_mfma_f32_16x16x32_bf16 v[20:23], v[200:203], v[172:175], v[20:23]
	v_mfma_f32_16x16x32_bf16 v[16:19], v[208:211], v[172:175], v[16:19]
	v_mfma_f32_16x16x32_bf16 v[12:15], v[200:203], v[180:183], v[12:15]
	v_mfma_f32_16x16x32_bf16 v[8:11], v[208:211], v[180:183], v[8:11]
	v_mfma_f32_16x16x32_bf16 v[4:7], v[200:203], v[188:191], v[4:7]
	v_mfma_f32_16x16x32_bf16 v[0:3], v[208:211], v[188:191], v[0:3]
	v_mfma_f32_16x16x32_bf16 v[28:31], v[204:207], v[168:171], v[28:31]
	v_mfma_f32_16x16x32_bf16 v[24:27], v[212:215], v[168:171], v[24:27]
	v_mfma_f32_16x16x32_bf16 v[20:23], v[204:207], v[176:179], v[20:23]
	v_mfma_f32_16x16x32_bf16 v[16:19], v[212:215], v[176:179], v[16:19]
	v_mfma_f32_16x16x32_bf16 v[12:15], v[204:207], v[184:187], v[12:15]
	v_mfma_f32_16x16x32_bf16 v[8:11], v[212:215], v[184:187], v[8:11]
	v_mfma_f32_16x16x32_bf16 v[4:7], v[204:207], v[192:195], v[4:7]
	v_mfma_f32_16x16x32_bf16 v[0:3], v[212:215], v[192:195], v[0:3]
	s_setprio 0
	s_barrier
	ds_read_b128 v[148:151], v145
	ds_read_b128 v[152:155], v145 offset:1024
	ds_read_b128 v[156:159], v145 offset:2048
	ds_read_b128 v[160:163], v145 offset:3072
	s_add_u32 s24, s24, 0x40000
	s_addc_u32 s25, s25, 0
	s_mov_b32 m0, s33
	v_lshl_add_u64 v[200:201], s[24:25], 0, v[130:131]
	ds_read_b128 v[164:167], v142 offset:32768
	ds_read_b128 v[168:171], v142 offset:33792
	ds_read_b128 v[172:175], v142 offset:34816
	ds_read_b128 v[176:179], v142 offset:35840
	ds_read_b128 v[180:183], v142 offset:36864
	ds_read_b128 v[184:187], v142 offset:37888
	ds_read_b128 v[188:191], v142 offset:38912
	ds_read_b128 v[192:195], v142 offset:39936
	global_load_lds_dwordx4 v[200:201], off
	v_lshl_add_u64 v[200:201], s[24:25], 0, v[128:129]
	s_mov_b32 m0, s34
	s_nop 0
	global_load_lds_dwordx4 v[200:201], off
	s_waitcnt lgkmcnt(8)
	s_barrier
	s_waitcnt lgkmcnt(0)
	s_setprio 1
	s_waitcnt lgkmcnt(0)
	v_mfma_f32_16x16x32_bf16 v[124:127], v[148:151], v[164:167], v[124:127]
	v_mfma_f32_16x16x32_bf16 v[120:123], v[156:159], v[164:167], v[120:123]
	v_mfma_f32_16x16x32_bf16 v[116:119], v[148:151], v[172:175], v[116:119]
	v_mfma_f32_16x16x32_bf16 v[112:115], v[156:159], v[172:175], v[112:115]
	v_mfma_f32_16x16x32_bf16 v[108:111], v[148:151], v[180:183], v[108:111]
	v_mfma_f32_16x16x32_bf16 v[104:107], v[156:159], v[180:183], v[104:107]
	v_mfma_f32_16x16x32_bf16 v[100:103], v[148:151], v[188:191], v[100:103]
	v_mfma_f32_16x16x32_bf16 v[96:99], v[156:159], v[188:191], v[96:99]
	v_mfma_f32_16x16x32_bf16 v[124:127], v[152:155], v[168:171], v[124:127]
	v_mfma_f32_16x16x32_bf16 v[120:123], v[160:163], v[168:171], v[120:123]
	v_mfma_f32_16x16x32_bf16 v[116:119], v[152:155], v[176:179], v[116:119]
	v_mfma_f32_16x16x32_bf16 v[112:115], v[160:163], v[176:179], v[112:115]
	v_mfma_f32_16x16x32_bf16 v[108:111], v[152:155], v[184:187], v[108:111]
	v_mfma_f32_16x16x32_bf16 v[104:107], v[160:163], v[184:187], v[104:107]
	v_mfma_f32_16x16x32_bf16 v[100:103], v[152:155], v[192:195], v[100:103]
	v_mfma_f32_16x16x32_bf16 v[96:99], v[160:163], v[192:195], v[96:99]
	s_setprio 0
	s_barrier
	s_mov_b32 m0, s36
	v_lshl_add_u64 v[196:197], v[196:197], 0, s[6:7]
	ds_read_b128 v[200:203], v146
	ds_read_b128 v[204:207], v146 offset:1024
	ds_read_b128 v[208:211], v146 offset:2048
	ds_read_b128 v[212:215], v146 offset:3072
	global_load_lds_dwordx4 v[196:197], off
	v_lshl_add_u64 v[196:197], v[216:217], 0, s[6:7]
	s_mov_b32 m0, s37
	s_nop 0
	global_load_lds_dwordx4 v[196:197], off
	s_barrier
	s_waitcnt lgkmcnt(0)
	s_setprio 1
	s_waitcnt lgkmcnt(0)
	v_mfma_f32_16x16x32_bf16 v[92:95], v[200:203], v[164:167], v[92:95]
	v_mfma_f32_16x16x32_bf16 v[88:91], v[208:211], v[164:167], v[88:91]
	v_mfma_f32_16x16x32_bf16 v[84:87], v[200:203], v[172:175], v[84:87]
	v_mfma_f32_16x16x32_bf16 v[80:83], v[208:211], v[172:175], v[80:83]
	v_mfma_f32_16x16x32_bf16 v[76:79], v[200:203], v[180:183], v[76:79]
	v_mfma_f32_16x16x32_bf16 v[72:75], v[208:211], v[180:183], v[72:75]
	v_mfma_f32_16x16x32_bf16 v[68:71], v[200:203], v[188:191], v[68:71]
	v_mfma_f32_16x16x32_bf16 v[64:67], v[208:211], v[188:191], v[64:67]
	v_mfma_f32_16x16x32_bf16 v[92:95], v[204:207], v[168:171], v[92:95]
	v_mfma_f32_16x16x32_bf16 v[88:91], v[212:215], v[168:171], v[88:91]
	v_mfma_f32_16x16x32_bf16 v[84:87], v[204:207], v[176:179], v[84:87]
	v_mfma_f32_16x16x32_bf16 v[80:83], v[212:215], v[176:179], v[80:83]
	v_mfma_f32_16x16x32_bf16 v[76:79], v[204:207], v[184:187], v[76:79]
	v_mfma_f32_16x16x32_bf16 v[72:75], v[212:215], v[184:187], v[72:75]
	v_mfma_f32_16x16x32_bf16 v[68:71], v[204:207], v[192:195], v[68:71]
	v_mfma_f32_16x16x32_bf16 v[64:67], v[212:215], v[192:195], v[64:67]
	s_setprio 0
	s_mov_b32 m0, s38
	v_lshl_add_u64 v[196:197], v[218:219], 0, s[6:7]
	s_barrier
	ds_read_b128 v[164:167], v142 offset:49152
	ds_read_b128 v[168:171], v142 offset:50176
	ds_read_b128 v[172:175], v142 offset:51200
	ds_read_b128 v[176:179], v142 offset:52224
	ds_read_b128 v[180:183], v142 offset:53248
	ds_read_b128 v[184:187], v142 offset:54272
	ds_read_b128 v[188:191], v142 offset:55296
	ds_read_b128 v[192:195], v142 offset:56320
	global_load_lds_dwordx4 v[196:197], off
	v_lshl_add_u64 v[196:197], v[220:221], 0, s[6:7]
	s_mov_b32 m0, s39
	s_nop 0
	global_load_lds_dwordx4 v[196:197], off
	s_barrier
	s_waitcnt lgkmcnt(0)
	s_setprio 1
	s_waitcnt lgkmcnt(0)
	v_mfma_f32_16x16x32_bf16 v[60:63], v[148:151], v[164:167], v[60:63]
	v_mfma_f32_16x16x32_bf16 v[56:59], v[156:159], v[164:167], v[56:59]
	v_mfma_f32_16x16x32_bf16 v[52:55], v[148:151], v[172:175], v[52:55]
	v_mfma_f32_16x16x32_bf16 v[48:51], v[156:159], v[172:175], v[48:51]
	v_mfma_f32_16x16x32_bf16 v[44:47], v[148:151], v[180:183], v[44:47]
	v_mfma_f32_16x16x32_bf16 v[40:43], v[156:159], v[180:183], v[40:43]
	v_mfma_f32_16x16x32_bf16 v[36:39], v[148:151], v[188:191], v[36:39]
	v_mfma_f32_16x16x32_bf16 v[32:35], v[156:159], v[188:191], v[32:35]
	v_mfma_f32_16x16x32_bf16 v[60:63], v[152:155], v[168:171], v[60:63]
	v_mfma_f32_16x16x32_bf16 v[56:59], v[160:163], v[168:171], v[56:59]
	v_mfma_f32_16x16x32_bf16 v[52:55], v[152:155], v[176:179], v[52:55]
	v_mfma_f32_16x16x32_bf16 v[48:51], v[160:163], v[176:179], v[48:51]
	v_mfma_f32_16x16x32_bf16 v[44:47], v[152:155], v[184:187], v[44:47]
	v_mfma_f32_16x16x32_bf16 v[40:43], v[160:163], v[184:187], v[40:43]
	v_mfma_f32_16x16x32_bf16 v[36:39], v[152:155], v[192:195], v[36:39]
	v_mfma_f32_16x16x32_bf16 v[32:35], v[160:163], v[192:195], v[32:35]
	s_setprio 0
	s_barrier
	s_add_u32 s22, s22, 0x40080
	s_addc_u32 s23, s23, 0
	s_mov_b32 m0, s40
	v_lshl_add_u64 v[148:149], s[22:23], 0, v[130:131]
	global_load_lds_dwordx4 v[148:149], off
	v_lshl_add_u64 v[148:149], s[22:23], 0, v[128:129]
	s_mov_b32 m0, s41
	s_nop 0
	global_load_lds_dwordx4 v[148:149], off
	s_waitcnt vmcnt(6)
	s_barrier
	s_setprio 1
	v_mfma_f32_16x16x32_bf16 v[28:31], v[200:203], v[164:167], v[28:31]
	v_mfma_f32_16x16x32_bf16 v[24:27], v[208:211], v[164:167], v[24:27]
	v_mfma_f32_16x16x32_bf16 v[20:23], v[200:203], v[172:175], v[20:23]
	v_mfma_f32_16x16x32_bf16 v[16:19], v[208:211], v[172:175], v[16:19]
	v_mfma_f32_16x16x32_bf16 v[12:15], v[200:203], v[180:183], v[12:15]
	v_mfma_f32_16x16x32_bf16 v[8:11], v[208:211], v[180:183], v[8:11]
	v_mfma_f32_16x16x32_bf16 v[4:7], v[200:203], v[188:191], v[4:7]
	v_mfma_f32_16x16x32_bf16 v[0:3], v[208:211], v[188:191], v[0:3]
	v_mfma_f32_16x16x32_bf16 v[28:31], v[204:207], v[168:171], v[28:31]
	v_mfma_f32_16x16x32_bf16 v[24:27], v[212:215], v[168:171], v[24:27]
	v_mfma_f32_16x16x32_bf16 v[20:23], v[204:207], v[176:179], v[20:23]
	v_mfma_f32_16x16x32_bf16 v[16:19], v[212:215], v[176:179], v[16:19]
	v_mfma_f32_16x16x32_bf16 v[12:15], v[204:207], v[184:187], v[12:15]
	v_mfma_f32_16x16x32_bf16 v[8:11], v[212:215], v[184:187], v[8:11]
	v_mfma_f32_16x16x32_bf16 v[4:7], v[204:207], v[192:195], v[4:7]
	v_mfma_f32_16x16x32_bf16 v[0:3], v[212:215], v[192:195], v[0:3]
	s_setprio 0
	s_add_i32 s50, s50, 2
	s_add_u32 s20, s20, 0x100
	s_addc_u32 s21, s21, 0
	s_add_u32 s48, s48, 0x100
	s_addc_u32 s49, s49, 0
	s_cmp_gt_u32 s50, 13
	s_barrier
	s_cbranch_scc0 .LBB0_983
	v_mov_b32_e32 v147, v198
	v_readlane_b32 s9, v252, 43
	v_readlane_b32 s15, v252, 45
	v_cvt_pk_bf16_f32 v124, v124, v125
	v_ashrrev_i32_e32 v149, 4, v147
	v_and_b32_e32 v132, 15, v147
	v_lshl_add_u32 v156, s9, 4, v149
	s_lshl_b32 s9, s9, 6
	v_lshlrev_b32_e32 v161, 8, v132
	v_lshlrev_b32_e32 v148, 4, v132
	v_lshl_add_u32 v132, v149, 3, s9
	v_xor_b32_e32 v162, v132, v148
	v_add_u32_e32 v132, 32, v132
	v_xor_b32_e32 v163, v132, v148
	v_xor_b32_e32 v132, v149, v147
	v_lshlrev_b32_e32 v132, 4, v132
	v_add_u32_e32 v149, 4, v156
	v_add_u32_e32 v160, 8, v156
	v_cvt_pk_bf16_f32 v125, v126, v127
	v_add3_u32 v126, s35, v162, v161
	v_cvt_pk_bf16_f32 v120, v120, v121
	v_cvt_pk_bf16_f32 v121, v122, v123
	v_add3_u32 v122, s35, v163, v161
	v_cvt_pk_bf16_f32 v116, v116, v117
	v_cvt_pk_bf16_f32 v117, v118, v119
	v_cvt_pk_bf16_f32 v112, v112, v113
	v_cvt_pk_bf16_f32 v113, v114, v115
	v_cvt_pk_bf16_f32 v108, v108, v109
	v_cvt_pk_bf16_f32 v109, v110, v111
	v_cvt_pk_bf16_f32 v104, v104, v105
	v_cvt_pk_bf16_f32 v105, v106, v107
	v_cvt_pk_bf16_f32 v100, v100, v101
	v_cvt_pk_bf16_f32 v101, v102, v103
	v_cvt_pk_bf16_f32 v96, v96, v97
	v_cvt_pk_bf16_f32 v97, v98, v99
	s_lshl_b32 s20, s4, 8
	s_lshl_b32 s15, s15, 6
	v_lshlrev_b32_e32 v164, 8, v156
	v_and_b32_e32 v165, 0xf0, v132
	v_xor_b32_e32 v150, v149, v147
	v_xor_b32_e32 v152, v160, v147
	ds_write_b64 v126, v[124:125]
	ds_write_b64 v122, v[120:121]
	ds_write_b64 v126, v[116:117] offset:4096
	ds_write_b64 v122, v[112:113] offset:4096
	ds_write_b64 v126, v[108:109] offset:8192
	ds_write_b64 v122, v[104:105] offset:8192
	ds_write_b64 v126, v[100:101] offset:12288
	ds_write_b64 v122, v[96:97] offset:12288
	s_add_i32 s15, s15, s20
	v_lshlrev_b32_e32 v150, 4, v150
	v_lshlrev_b32_e32 v152, 4, v152
	v_add_u32_e32 v170, 12, v156
	s_waitcnt lgkmcnt(0)
	s_barrier
	v_add3_u32 v114, s35, v165, v164
	v_add_lshl_u32 v132, s15, v156, 10
	v_and_b32_e32 v167, 0xf0, v150
	v_add_lshl_u32 v150, v149, s15, 10
	v_and_b32_e32 v169, 0xf0, v152
	v_add_lshl_u32 v152, v160, s15, 10
	v_add_lshl_u32 v154, v170, s15, 10
	s_addk_i32 s15, 0x80
	ds_read_b128 v[96:99], v114
	v_lshlrev_b32_e32 v166, 8, v149
	v_add_lshl_u32 v158, s15, v149, 10
	v_mov_b32_e32 v149, v133
	s_lshl_b32 s4, s45, 8
	v_xor_b32_e32 v147, v170, v147
	v_lshl_add_u64 v[148:149], s[10:11], 0, v[148:149]
	v_lshlrev_b32_e32 v168, 8, v160
	v_lshlrev_b32_e32 v147, 4, v147
	v_lshl_add_u64 v[108:109], s[4:5], 1, v[148:149]
	v_add3_u32 v115, s35, v167, v166
	v_lshlrev_b32_e32 v171, 8, v170
	v_and_b32_e32 v147, 0xf0, v147
	v_lshl_add_u64 v[110:111], v[132:133], 1, v[108:109]
	ds_read_b128 v[100:103], v115
	v_add3_u32 v116, s35, v169, v168
	s_waitcnt lgkmcnt(0)
	global_store_dwordx4 v[110:111], v[96:99], off sc1
	ds_read_b128 v[96:99], v116
	v_add3_u32 v117, s35, v147, v171
	ds_read_b128 v[104:107], v117
	v_mov_b32_e32 v151, v133
	v_mov_b32_e32 v153, v133
	v_lshl_add_u64 v[112:113], v[150:151], 1, v[108:109]
	v_mov_b32_e32 v155, v133
	global_store_dwordx4 v[112:113], v[100:103], off sc1
	v_cvt_pk_bf16_f32 v92, v92, v93
	v_cvt_pk_bf16_f32 v93, v94, v95
	v_lshl_add_u64 v[100:101], v[152:153], 1, v[108:109]
	s_waitcnt lgkmcnt(0)
	global_store_dwordx4 v[100:101], v[96:99], off sc1
	v_cvt_pk_bf16_f32 v88, v88, v89
	v_cvt_pk_bf16_f32 v89, v90, v91
	v_lshl_add_u64 v[96:97], v[154:155], 1, v[108:109]
	global_store_dwordx4 v[96:97], v[104:107], off sc1
	v_cvt_pk_bf16_f32 v84, v84, v85
	v_cvt_pk_bf16_f32 v85, v86, v87
	v_cvt_pk_bf16_f32 v80, v80, v81
	v_cvt_pk_bf16_f32 v81, v82, v83
	v_cvt_pk_bf16_f32 v76, v76, v77
	v_cvt_pk_bf16_f32 v77, v78, v79
	v_cvt_pk_bf16_f32 v72, v72, v73
	v_cvt_pk_bf16_f32 v73, v74, v75
	v_cvt_pk_bf16_f32 v68, v68, v69
	v_cvt_pk_bf16_f32 v69, v70, v71
	v_cvt_pk_bf16_f32 v64, v64, v65
	v_cvt_pk_bf16_f32 v65, v66, v67
	s_waitcnt lgkmcnt(0)
	s_barrier
	ds_write_b64 v126, v[92:93]
	ds_write_b64 v122, v[88:89]
	ds_write_b64 v126, v[84:85] offset:4096
	ds_write_b64 v122, v[80:81] offset:4096
	ds_write_b64 v126, v[76:77] offset:8192
	ds_write_b64 v122, v[72:73] offset:8192
	ds_write_b64 v126, v[68:69] offset:12288
	ds_write_b64 v122, v[64:65] offset:12288
	s_waitcnt lgkmcnt(0)
	s_barrier
	ds_read_b128 v[64:67], v114
	ds_read_b128 v[68:71], v115
	ds_read_b128 v[72:75], v116
	ds_read_b128 v[76:79], v117
	s_waitcnt lgkmcnt(0)
	global_store_dwordx4 v[110:111], v[64:67], off offset:256 sc1
	global_store_dwordx4 v[112:113], v[68:71], off offset:256 sc1
	global_store_dwordx4 v[100:101], v[72:75], off offset:256 sc1
	global_store_dwordx4 v[96:97], v[76:79], off offset:256 sc1
	v_cvt_pk_bf16_f32 v60, v60, v61
	v_cvt_pk_bf16_f32 v61, v62, v63
	v_cvt_pk_bf16_f32 v56, v56, v57
	v_cvt_pk_bf16_f32 v57, v58, v59
	v_cvt_pk_bf16_f32 v52, v52, v53
	v_cvt_pk_bf16_f32 v53, v54, v55
	v_cvt_pk_bf16_f32 v48, v48, v49
	v_cvt_pk_bf16_f32 v49, v50, v51
	v_cvt_pk_bf16_f32 v44, v44, v45
	v_cvt_pk_bf16_f32 v45, v46, v47
	v_cvt_pk_bf16_f32 v40, v40, v41
	v_cvt_pk_bf16_f32 v41, v42, v43
	v_cvt_pk_bf16_f32 v36, v36, v37
	v_cvt_pk_bf16_f32 v37, v38, v39
	v_cvt_pk_bf16_f32 v32, v32, v33
	v_cvt_pk_bf16_f32 v33, v34, v35
	s_waitcnt lgkmcnt(0)
	s_barrier
	ds_write_b64 v126, v[60:61]
	ds_write_b64 v122, v[56:57]
	ds_write_b64 v126, v[52:53] offset:4096
	ds_write_b64 v122, v[48:49] offset:4096
	ds_write_b64 v126, v[44:45] offset:8192
	ds_write_b64 v122, v[40:41] offset:8192
	ds_write_b64 v126, v[36:37] offset:12288
	ds_write_b64 v122, v[32:33] offset:12288
	s_waitcnt lgkmcnt(0)
	s_barrier
	ds_read_b128 v[32:35], v114
	ds_read_b128 v[36:39], v115
	v_add_lshl_u32 v156, s15, v156, 10
	v_mov_b32_e32 v157, v133
	v_lshl_add_u64 v[46:47], v[156:157], 1, v[108:109]
	s_waitcnt lgkmcnt(0)
	global_store_dwordx4 v[46:47], v[32:35], off sc1
	ds_read_b128 v[32:35], v116
	ds_read_b128 v[40:43], v117
	v_mov_b32_e32 v159, v133
	v_add_lshl_u32 v160, s15, v160, 10
	v_mov_b32_e32 v161, v133
	v_lshl_add_u64 v[48:49], v[158:159], 1, v[108:109]
	v_add_lshl_u32 v44, s15, v170, 10
	v_mov_b32_e32 v45, v133
	global_store_dwordx4 v[48:49], v[36:39], off sc1
	v_cvt_pk_bf16_f32 v28, v28, v29
	v_cvt_pk_bf16_f32 v29, v30, v31
	v_lshl_add_u64 v[36:37], v[160:161], 1, v[108:109]
	s_waitcnt lgkmcnt(0)
	global_store_dwordx4 v[36:37], v[32:35], off sc1
	v_cvt_pk_bf16_f32 v24, v24, v25
	v_cvt_pk_bf16_f32 v25, v26, v27
	v_lshl_add_u64 v[32:33], v[44:45], 1, v[108:109]
	global_store_dwordx4 v[32:33], v[40:43], off sc1
	v_cvt_pk_bf16_f32 v20, v20, v21
	v_cvt_pk_bf16_f32 v21, v22, v23
	v_cvt_pk_bf16_f32 v16, v16, v17
	v_cvt_pk_bf16_f32 v17, v18, v19
	v_cvt_pk_bf16_f32 v12, v12, v13
	v_cvt_pk_bf16_f32 v13, v14, v15
	v_cvt_pk_bf16_f32 v8, v8, v9
	v_cvt_pk_bf16_f32 v9, v10, v11
	v_cvt_pk_bf16_f32 v4, v4, v5
	v_cvt_pk_bf16_f32 v5, v6, v7
	v_cvt_pk_bf16_f32 v0, v0, v1
	v_cvt_pk_bf16_f32 v1, v2, v3
	s_waitcnt lgkmcnt(0)
	s_barrier
	ds_write_b64 v126, v[28:29]
	ds_write_b64 v122, v[24:25]
	ds_write_b64 v126, v[20:21] offset:4096
	ds_write_b64 v122, v[16:17] offset:4096
	ds_write_b64 v126, v[12:13] offset:8192
	ds_write_b64 v122, v[8:9] offset:8192
	ds_write_b64 v126, v[4:5] offset:12288
	ds_write_b64 v122, v[0:1] offset:12288
	s_waitcnt lgkmcnt(0)
	s_barrier
	ds_read_b128 v[0:3], v114
	ds_read_b128 v[4:7], v115
	ds_read_b128 v[8:11], v116
	ds_read_b128 v[12:15], v117
	s_waitcnt lgkmcnt(0)
	global_store_dwordx4 v[46:47], v[0:3], off offset:256 sc1
	global_store_dwordx4 v[48:49], v[4:7], off offset:256 sc1
	global_store_dwordx4 v[36:37], v[8:11], off offset:256 sc1
	global_store_dwordx4 v[32:33], v[12:15], off offset:256 sc1
	s_waitcnt lgkmcnt(0)
	s_barrier
	s_cmp_lt_u32 s44, 2
	s_cbranch_scc1 .Lp5_nosig
	s_waitcnt vmcnt(0)
	s_barrier
	s_barrier
	v_readlane_b32 s98, v252, 35
	v_readlane_b32 s99, v252, 36
	s_and_b64 vcc, exec, s[98:99]
	s_cbranch_vccnz .Lp5_nosig
	s_waitcnt vmcnt(0)
	v_readlane_b32 s100, v252, 25
	v_readlane_b32 s101, v252, 26
	s_cmp_eq_u32 s44, 2
	s_movk_i32 s98, 0x300
	s_cselect_b32 s98, 0x100, s98
	v_mov_b32_e32 v254, s98
	v_mov_b32_e32 v255, 1
	s_mov_b64 s[98:99], exec
	s_mov_b64 exec, 1
	s_nop 1
	global_atomic_add v254, v255, s[100:101]
	s_waitcnt vmcnt(0)
	s_mov_b64 exec, s[98:99]

.LBB0_1049:
	s_barrier
	v_readlane_b32 s0, v252, 17
	s_mov_b32 s98, 0
	s_nop 2
	s_lshr_b32 s1, s0, 13
	s_add_i32 s2, s1, 1
	s_lshl_b32 s101, 1, s2
	s_cmp_lt_u32 s1, 7
	s_cselect_b32 s101, s101, 0
	s_cmp_eq_u32 s1, 1
	s_cselect_b32 s2, 0x100, 0
	s_or_b32 s101, s101, s2
	s_xor_b32 s100, s101, 0x1ff
	s_cmp_lt_u32 s0, 0x1000
	s_cbranch_scc1 .LBB0_1052
.Lp6_pass:
	s_mov_b32 s99, -1
	s_nop 0
	v_add_u32_e32 v0, s0, v240
	v_ashrrev_i32_e32 v0, 5, v0
	v_and_b32_e32 v16, -2, v0
	s_mov_b32 s0, 0x8200
	v_cmp_gt_i32_e32 vcc, s0, v16
	s_and_saveexec_b64 s[0:1], vcc
	s_xor_b64 s[0:1], exec, s[0:1]
	s_cbranch_execz .LBB0_1052
	v_ashrrev_i32_e32 v17, 31, v16
	v_lshlrev_b64 v[2:3], 12, v[16:17]
	v_and_b32_e32 v1, 63, v240
	v_lshl_or_b32 v2, v1, 4, v2
	v_lshl_add_u64 v[2:3], s[74:75], 0, v[2:3]
	s_mov_b64 s[0:1], 0x1000
	v_lshlrev_b32_e32 v0, 2, v240
	v_lshl_add_u64 v[22:23], v[2:3], 0, s[0:1]
	v_lshlrev_b64 v[2:3], 11, v[16:17]
	v_and_b32_e32 v0, 0xfc, v0
	s_lshl_b32 s0, s90, 4
	v_lshl_or_b32 v2, v1, 3, v2
	v_mov_b32_e32 v19, 0
	v_lshlrev_b32_e32 v18, 2, v0
	s_bfe_i32 s3, s0, 0x1001a
	s_bfe_i32 s2, s0, 0x1b0000
	v_lshl_add_u64 v[2:3], s[88:89], 0, v[2:3]
	s_mov_b64 s[0:1], 0x12e80e00
	s_ashr_i32 s11, s96, 5
	v_lshl_add_u64 v[20:21], s[72:73], 0, v[18:19]
	s_lshl_b64 s[4:5], s[2:3], 12
	v_lshl_add_u64 v[24:25], v[2:3], 0, s[0:1]
	s_lshl_b64 s[6:7], s[2:3], 11
	v_lshl_add_u64 v[26:27], v[16:17], 0, 1
	s_mov_b64 s[8:9], 0
	s_mov_b32 s12, 0x8000
	v_mov_b32_e32 v17, s59
	v_mov_b32_e32 v29, s57
	v_mov_b32_e32 v50, s58
	v_mov_b32_e32 v51, s56
	v_lshlrev_b32_e32 v18, 2, v0
	s_mov_b32 s10, 0x3a800000
	v_mov_b32_e32 v28, 0x358637bd
	s_mov_b32 s13, 0x800000
	s_mov_b32 s14, 0x81ff
.LBB0_1051:
	s_add_i32 s99, s99, 1
	s_bitcmp1_b32 s100, s99
	s_cbranch_scc0 .Lp6_skip
	v_lshl_add_u64 v[46:47], v[26:27], 0, -1
	v_cmp_gt_i32_e32 vcc, s12, v16
	v_add_u32_e32 v48, 0xffff8000, v16
	v_add_u32_e32 v54, 0xffff8001, v16
	v_cmp_gt_i32_e64 s[0:1], s12, v26
	v_cndmask_b32_e32 v47, 0, v47, vcc
	v_cndmask_b32_e32 v46, v48, v46, vcc
	v_cndmask_b32_e64 v49, 0, v27, s[0:1]
	v_cndmask_b32_e32 v53, v17, v29, vcc
	v_cndmask_b32_e32 v52, v50, v51, vcc
	v_cndmask_b32_e64 v48, v54, v26, s[0:1]
	v_lshlrev_b64 v[46:47], 12, v[46:47]
	global_load_dwordx2 v[36:37], v[24:25], off offset:-3584 nt
	global_load_dwordx2 v[34:35], v[24:25], off offset:-3072 nt
	global_load_dwordx2 v[32:33], v[24:25], off offset:-2560 nt
	global_load_dwordx2 v[30:31], v[24:25], off offset:-2048 nt
	v_cndmask_b32_e64 v55, v17, v29, s[0:1]
	v_cndmask_b32_e64 v54, v50, v51, s[0:1]
	v_lshlrev_b64 v[48:49], 12, v[48:49]
	v_lshl_add_u64 v[46:47], v[52:53], 0, v[46:47]
	v_lshl_add_u64 v[48:49], v[54:55], 0, v[48:49]
	v_lshl_add_u64 v[80:81], v[46:47], 0, v[18:19]
	global_load_dwordx2 v[44:45], v[24:25], off offset:-1536 nt
	global_load_dwordx2 v[42:43], v[24:25], off offset:-1024 nt
	global_load_dwordx2 v[40:41], v[24:25], off offset:-512 nt
	global_load_dwordx2 v[38:39], v[24:25], off nt
	global_load_dwordx4 v[12:15], v[20:21], off
	global_load_dwordx4 v[8:11], v[20:21], off offset:1024
	global_load_dwordx4 v[4:7], v[20:21], off offset:2048
	global_load_dwordx4 v[0:3], v[20:21], off offset:3072
	v_lshl_add_u64 v[82:83], v[48:49], 0, v[18:19]
	global_load_dwordx4 v[46:49], v[80:81], off nt
	global_load_dwordx4 v[52:55], v[80:81], off offset:1024 nt
	global_load_dwordx4 v[56:59], v[80:81], off offset:2048 nt
	global_load_dwordx4 v[60:63], v[80:81], off offset:3072 nt
	global_load_dwordx4 v[64:67], v[82:83], off nt
	global_load_dwordx4 v[68:71], v[82:83], off offset:1024 nt
	global_load_dwordx4 v[72:75], v[82:83], off offset:2048 nt
	global_load_dwordx4 v[76:79], v[82:83], off offset:3072 nt
	v_add_u32_e32 v16, s11, v16
	v_cmp_lt_i32_e32 vcc, s14, v16
	s_or_b64 s[8:9], vcc, s[8:9]
	v_lshl_add_u64 v[24:25], v[24:25], 0, s[6:7]
	v_lshl_add_u64 v[26:27], v[26:27], 0, s[2:3]
	s_waitcnt vmcnt(19)
	v_and_b32_e32 v81, 0xffff0000, v36
	v_lshlrev_b32_e32 v80, 16, v36
	v_and_b32_e32 v83, 0xffff0000, v37
	v_lshlrev_b32_e32 v82, 16, v37
	s_waitcnt vmcnt(18)
	v_and_b32_e32 v37, 0xffff0000, v34
	v_lshlrev_b32_e32 v36, 16, v34
	v_and_b32_e32 v85, 0xffff0000, v35
	v_lshlrev_b32_e32 v84, 16, v35
	s_waitcnt vmcnt(17)
	v_and_b32_e32 v35, 0xffff0000, v32
	v_lshlrev_b32_e32 v34, 16, v32
	v_and_b32_e32 v87, 0xffff0000, v33
	v_lshlrev_b32_e32 v86, 16, v33
	s_waitcnt vmcnt(16)
	v_and_b32_e32 v33, 0xffff0000, v30
	v_lshlrev_b32_e32 v32, 16, v30
	v_and_b32_e32 v89, 0xffff0000, v31
	v_lshlrev_b32_e32 v88, 16, v31
	s_waitcnt vmcnt(15)
	v_and_b32_e32 v31, 0xffff0000, v44
	v_lshlrev_b32_e32 v30, 16, v44
	v_and_b32_e32 v91, 0xffff0000, v45
	v_lshlrev_b32_e32 v90, 16, v45
	s_waitcnt vmcnt(14)
	v_and_b32_e32 v45, 0xffff0000, v42
	v_lshlrev_b32_e32 v44, 16, v42
	v_and_b32_e32 v93, 0xffff0000, v43
	v_lshlrev_b32_e32 v92, 16, v43
	s_waitcnt vmcnt(13)
	v_and_b32_e32 v43, 0xffff0000, v40
	v_lshlrev_b32_e32 v42, 16, v40
	v_and_b32_e32 v95, 0xffff0000, v41
	v_lshlrev_b32_e32 v94, 16, v41
	s_waitcnt vmcnt(12)
	v_and_b32_e32 v41, 0xffff0000, v38
	v_lshlrev_b32_e32 v40, 16, v38
	v_and_b32_e32 v97, 0xffff0000, v39
	v_lshlrev_b32_e32 v96, 16, v39
	s_waitcnt vmcnt(7)
	v_pk_add_f32 v[38:39], v[46:47], v[80:81]
	s_waitcnt vmcnt(6)
	v_pk_add_f32 v[36:37], v[52:53], v[36:37]
	s_waitcnt vmcnt(5)
	v_pk_add_f32 v[34:35], v[56:57], v[34:35]
	s_waitcnt vmcnt(4)
	v_pk_add_f32 v[32:33], v[60:61], v[32:33]
	s_waitcnt vmcnt(3)
	v_pk_add_f32 v[30:31], v[64:65], v[30:31]
	s_waitcnt vmcnt(2)
	v_pk_add_f32 v[44:45], v[68:69], v[44:45]
	v_pk_add_f32 v[46:47], v[48:49], v[82:83]
	v_pk_add_f32 v[56:57], v[66:67], v[90:91]
	s_waitcnt vmcnt(1)
	v_pk_add_f32 v[42:43], v[72:73], v[42:43]
	v_pk_add_f32 v[60:61], v[74:75], v[94:95]
	s_waitcnt vmcnt(0)
	v_pk_add_f32 v[40:41], v[76:77], v[40:41]
	v_mov_b32_e32 v66, v39
	v_mov_b32_e32 v67, v37
	v_mov_b32_e32 v74, v35
	v_mov_b32_e32 v75, v33
	v_mov_b32_e32 v82, v31
	v_mov_b32_e32 v83, v45
	v_pk_add_f32 v[48:49], v[54:55], v[84:85]
	v_pk_add_f32 v[52:53], v[58:59], v[86:87]
	v_pk_add_f32 v[58:59], v[70:71], v[92:93]
	v_mov_b32_e32 v64, v38
	v_mov_b32_e32 v65, v36
	v_mov_b32_e32 v72, v34
	v_mov_b32_e32 v73, v32
	v_mov_b32_e32 v80, v30
	v_mov_b32_e32 v81, v44
	v_mov_b32_e32 v90, v43
	v_mov_b32_e32 v91, v41
	v_pk_mul_f32 v[66:67], v[66:67], v[66:67]
	v_pk_mul_f32 v[74:75], v[74:75], v[74:75]
	v_pk_mul_f32 v[82:83], v[82:83], v[82:83]
	v_pk_add_f32 v[54:55], v[62:63], v[88:89]
	v_pk_add_f32 v[62:63], v[78:79], v[96:97]
	v_mov_b32_e32 v68, v46
	v_mov_b32_e32 v69, v48
	v_mov_b32_e32 v84, v56
	v_mov_b32_e32 v85, v58
	v_mov_b32_e32 v88, v42
	v_mov_b32_e32 v89, v40
	v_pk_mul_f32 v[90:91], v[90:91], v[90:91]
	v_pk_fma_f32 v[64:65], v[64:65], v[64:65], v[66:67]
	v_pk_fma_f32 v[66:67], v[72:73], v[72:73], v[74:75]
	v_pk_fma_f32 v[72:73], v[80:81], v[80:81], v[82:83]
	v_mov_b32_e32 v70, v47
	v_mov_b32_e32 v71, v49
	v_mov_b32_e32 v76, v52
	v_mov_b32_e32 v77, v54
	v_mov_b32_e32 v86, v57
	v_mov_b32_e32 v87, v59
	v_mov_b32_e32 v92, v60
	v_mov_b32_e32 v93, v62
	v_pk_fma_f32 v[74:75], v[88:89], v[88:89], v[90:91]
	v_pk_fma_f32 v[64:65], v[68:69], v[68:69], v[64:65]
	v_pk_fma_f32 v[68:69], v[84:85], v[84:85], v[72:73]
	v_mov_b32_e32 v78, v53
	v_mov_b32_e32 v79, v55
	v_mov_b32_e32 v94, v61
	v_mov_b32_e32 v95, v63
	v_pk_fma_f32 v[66:67], v[76:77], v[76:77], v[66:67]
	v_pk_fma_f32 v[72:73], v[92:93], v[92:93], v[74:75]
	v_pk_fma_f32 v[64:65], v[70:71], v[70:71], v[64:65]
	v_pk_fma_f32 v[68:69], v[86:87], v[86:87], v[68:69]
	v_pk_fma_f32 v[66:67], v[78:79], v[78:79], v[66:67]
	v_pk_fma_f32 v[70:71], v[94:95], v[94:95], v[72:73]
	v_mov_b32_e32 v72, v68
	v_mov_b32_e32 v73, v64
	v_mov_b32_e32 v64, v69
	v_mov_b32_e32 v68, v70
	v_mov_b32_e32 v69, v66
	v_pk_add_f32 v[64:65], v[72:73], v[64:65]
	v_mov_b32_e32 v66, v71
	v_pk_add_f32 v[64:65], v[64:65], v[68:69]
	s_nop 0
	v_pk_add_f32 v[64:65], v[64:65], v[66:67]
	ds_bpermute_b32 v67, v234, v65
	ds_bpermute_b32 v66, v234, v64
	s_waitcnt lgkmcnt(0)
	v_pk_add_f32 v[64:65], v[64:65], v[66:67]
	ds_bpermute_b32 v67, v235, v65
	ds_bpermute_b32 v66, v235, v64
	s_waitcnt lgkmcnt(0)
	v_pk_add_f32 v[64:65], v[64:65], v[66:67]
	ds_bpermute_b32 v67, v236, v65
	ds_bpermute_b32 v66, v236, v64
	s_waitcnt lgkmcnt(0)
	v_pk_add_f32 v[64:65], v[64:65], v[66:67]
	ds_bpermute_b32 v67, v237, v65
	ds_bpermute_b32 v66, v237, v64
	s_waitcnt lgkmcnt(0)
	v_pk_add_f32 v[64:65], v[64:65], v[66:67]
	ds_bpermute_b32 v67, v238, v65
	ds_bpermute_b32 v66, v238, v64
	s_waitcnt lgkmcnt(0)
	v_pk_add_f32 v[64:65], v[64:65], v[66:67]
	ds_bpermute_b32 v67, v239, v65
	ds_bpermute_b32 v66, v239, v64
	s_waitcnt lgkmcnt(0)
	v_pk_add_f32 v[64:65], v[64:65], v[66:67]
	s_nop 0
	v_pk_fma_f32 v[64:65], v[64:65], s[10:11], v[28:29] op_sel_hi:[1,0,0]
	s_nop 0
	v_mul_f32_e32 v66, 0x4b800000, v65
	v_cmp_gt_f32_e64 s[0:1], s13, v65
	v_mul_f32_e32 v67, 0x4b800000, v64
	v_cmp_gt_f32_e32 vcc, s13, v64
	v_cndmask_b32_e64 v65, v65, v66, s[0:1]
	v_rsq_f32_e32 v65, v65
	v_cndmask_b32_e32 v64, v64, v67, vcc
	v_rsq_f32_e32 v66, v64
	v_mul_f32_e32 v64, 0x45800000, v65
	v_cndmask_b32_e64 v64, v65, v64, s[0:1]
	v_mul_f32_e32 v67, 0x45800000, v66
	v_cndmask_b32_e32 v66, v66, v67, vcc
	v_pk_mul_f32 v[38:39], v[38:39], v[64:65] op_sel_hi:[1,0]
	v_pk_mul_f32 v[46:47], v[46:47], v[64:65] op_sel_hi:[1,0]
	v_pk_mul_f32 v[68:69], v[36:37], v[64:65] op_sel_hi:[1,0]
	v_pk_mul_f32 v[36:37], v[48:49], v[64:65] op_sel_hi:[1,0]
	v_pk_mul_f32 v[48:49], v[34:35], v[64:65] op_sel_hi:[1,0]
	v_pk_mul_f32 v[52:53], v[52:53], v[64:65] op_sel_hi:[1,0]
	v_pk_mul_f32 v[70:71], v[32:33], v[64:65] op_sel_hi:[1,0]
	v_pk_mul_f32 v[54:55], v[54:55], v[64:65] op_sel_hi:[1,0]
	v_pk_mul_f32 v[64:65], v[30:31], v[66:67] op_sel_hi:[1,0]
	v_pk_mul_f32 v[56:57], v[56:57], v[66:67] op_sel_hi:[1,0]
	v_pk_mul_f32 v[72:73], v[44:45], v[66:67] op_sel_hi:[1,0]
	v_pk_mul_f32 v[58:59], v[58:59], v[66:67] op_sel_hi:[1,0]
	v_pk_mul_f32 v[74:75], v[42:43], v[66:67] op_sel_hi:[1,0]
	v_pk_mul_f32 v[60:61], v[60:61], v[66:67] op_sel_hi:[1,0]
	v_pk_mul_f32 v[76:77], v[40:41], v[66:67] op_sel_hi:[1,0]
	v_pk_mul_f32 v[62:63], v[62:63], v[66:67] op_sel_hi:[1,0]
	v_pk_mul_f32 v[32:33], v[14:15], v[46:47]
	v_pk_mul_f32 v[30:31], v[12:13], v[38:39]
	v_pk_mul_f32 v[36:37], v[10:11], v[36:37]
	v_pk_mul_f32 v[34:35], v[8:9], v[68:69]
	v_pk_mul_f32 v[40:41], v[6:7], v[52:53]
	v_pk_mul_f32 v[38:39], v[4:5], v[48:49]
	v_pk_mul_f32 v[44:45], v[2:3], v[54:55]
	v_pk_mul_f32 v[42:43], v[0:1], v[70:71]
	v_pk_mul_f32 v[14:15], v[14:15], v[56:57]
	v_pk_mul_f32 v[12:13], v[12:13], v[64:65]
	v_pk_mul_f32 v[10:11], v[10:11], v[58:59]
	v_pk_mul_f32 v[8:9], v[8:9], v[72:73]
	v_pk_mul_f32 v[6:7], v[6:7], v[60:61]
	v_pk_mul_f32 v[4:5], v[4:5], v[74:75]
	v_pk_mul_f32 v[2:3], v[2:3], v[62:63]
	v_pk_mul_f32 v[0:1], v[0:1], v[76:77]
	global_store_dwordx4 v[22:23], v[30:33], off offset:-4096 nt
	global_store_dwordx4 v[22:23], v[34:37], off offset:-3072 nt
	global_store_dwordx4 v[22:23], v[38:41], off offset:-2048 nt
	global_store_dwordx4 v[22:23], v[42:45], off offset:-1024 nt
	global_store_dwordx4 v[22:23], v[12:15], off nt
	global_store_dwordx4 v[22:23], v[8:11], off offset:1024 nt
	global_store_dwordx4 v[22:23], v[4:7], off offset:2048 nt
	global_store_dwordx4 v[22:23], v[0:3], off offset:3072 nt
	v_lshl_add_u64 v[22:23], v[22:23], 0, s[4:5]
	s_andn2_b64 exec, exec, s[8:9]
	s_cbranch_execnz .LBB0_1051
	s_branch .Lp6_passend

.Lp6_passend:
	s_mov_b64 exec, -1
	s_add_i32 s98, s98, 1
	s_cmp_eq_u32 s98, 1
	s_cbranch_scc0 .Lp6_after2
	s_cmp_eq_u32 s101, 0
	s_cbranch_scc1 .LBB0_1052
	s_mov_b32 s100, s101
	v_readlane_b32 s0, v252, 35
	v_readlane_b32 s1, v252, 36
	s_and_b64 vcc, exec, s[0:1]
	s_cbranch_vccnz .Lp6_gotB
	v_readlane_b32 s2, v252, 25
	v_readlane_b32 s3, v252, 26
	v_mov_b32_e32 v0, 0
	s_mov_b32 s9, 0
	s_nop 2

.Lp6_gotB:
	s_barrier
	v_readlane_b32 s0, v252, 17
	s_branch .Lp6_pass
.Lp6_after2:
	s_cmp_eq_u32 s98, 2
	s_cbranch_scc0 .LBB0_1052
	v_readlane_b32 s0, v252, 17
	s_nop 2
	s_lshr_b32 s1, s0, 9
	s_sub_u32 s1, s1, 32
	s_cmp_lt_u32 s1, 72
	s_cbranch_scc0 .LBB0_1052
	s_lshr_b32 s2, s1, 3
	s_lshl_b32 s100, 1, s2
	s_and_b32 s1, s1, 7
	s_lshl_b32 s0, s1, 9
	s_branch .Lp6_pass
